# GEMM closing barrier one MFMA before the block end, wave at priority 2 across it
# speedup vs baseline: 1.0872x; 1.0872x over previous
;     __device__ __forceinline__ void stage_rs(const Unit& u, int tid, int wid) const { stage_rs_lds(SS, rsl, u, tid, wid); }
;     __device__ __forceinline__ void stage_rs(const Unit& u, int tid, int wid) const { stage_rs_lds(SS, rsl, u, tid, wid); }
; #define PG8_STAGE(bufoff, gbase, voff) do { _Pragma("unroll") for (int _i = 0; _i < 2; ++_i) \
;         __builtin_amdgcn_global_load_lds((const unsigned*)((const char*)(gbase) + (voff)[_i]), (PG8_LAS unsigned*)(lds + (bufoff) + ldsw + _i * 8192), 16, 0, 0); } while (0)
; #define PG8_LDA(dst, b, h) do { _Pragma("unroll") for (int m = 0; m < 4; ++m) _Pragma("unroll") for (int k = 0; k < 2; ++k) dst[m][k] = *(const PG8_LAS bf16x8*)(lds + PG8_SA(b, h) + aoff + m * 2048 + k * 1024); } while (0)
; #define PG8_LDB(dst, b, h) do { _Pragma("unroll") for (int n = 0; n < 2; ++n) _Pragma("unroll") for (int k = 0; k < 2; ++k) dst[n][k] = *(const PG8_LAS bf16x8*)(lds + PG8_SB(b, h) + boff + n * 2048 + k * 1024); } while (0)
; #define PG8_BAR __builtin_amdgcn_s_barrier()
; template <class Epi, class Sched, bool ALIGN_EPI = false, bool SP2 = false>
; __device__ __forceinline__ void gemm_phase(PG8_LAS unsigned char* lds, const Gemm g, const Sched& S, const Epi& E, const int tid) {
;     ...
;         for (int t = 0; t < nt; t += 2) {
;             const bool last = (t == nt - 2);
;             if constexpr (Epi::RS_LDS) { if (t == nt - 4) E.stage_rs(cur, tid, wid); }
;             if constexpr (Epi::PREFETCH) { if (t >= nt - 8) E.prefetch(cur, lds, tid, wid, (t - (nt - 8)) >> 1); }
;             const char* a1 = cA + (size_t)(t + 1) * kstep;
;             const char* a2 = last ? nA : cA + (size_t)(t + 2) * kstep; const char* b2 = last ? nB : cB + (size_t)(t + 2) * kstep;
;             const char* a3 = a2 + kstep; const char* b3 = b2 + kstep;
;             if (last && has_next) S.a_ready(nxt);
;             if constexpr (SP2) {
;             PG8_LDB(B0, 0, 0); PG8_LDB(B1, 0, 1); PG8_SCHED; PG8_LDA(At, 0, 0); PG8_STAGE(PG8_SA(1, 1), a1 + hstep, voffA);
;             PG8_WAIT_V(8); PG8_WAIT_L(0); PG8_BAR; PG8_MMA(0, 0, At, B0); PG8_MMA(0, 1, At, B1); PG8_BAR; PG8_SCHED;
;             PG8_LDA(At, 0, 1); PG8_STAGE(PG8_SB(0, 0), b2, voffB); PG8_STAGE(PG8_SB(0, 1), b2 + hstep, voffB); PG8_STAGE(PG8_SA(0, 0), a2, voffA);
;             PG8_WAIT_V(8); PG8_WAIT_L(0); PG8_BAR; PG8_MMA(1, 0, At, B0); PG8_MMA(1, 1, At, B1); PG8_BAR; PG8_SCHED;
.LBB0_87:
	s_add_u32 s38, s22, s68
	s_addc_u32 s39, s23, s69
	s_add_u32 s38, s38, 0x100
	s_addc_u32 s39, s39, 0
	s_add_u32 s50, s89, s68
	s_addc_u32 s51, s90, s69
	s_add_i32 s92, 0, 0x10000
	s_cmpk_eq_i32 s68, 0x700
	s_cselect_b32 s73, s15, s39
	s_cselect_b32 s72, s86, s38
	v_add_u32_e32 v150, s92, v153
	s_cselect_b32 s71, s87, s51
	s_cselect_b32 s70, s88, s50
	s_add_i32 s38, 0, 0x14000
	ds_read_b128 v[170:173], v150
	ds_read_b128 v[174:177], v150 offset:1024
	ds_read_b128 v[178:181], v150 offset:2048
	ds_read_b128 v[182:185], v150 offset:3072
	v_add_u32_e32 v150, s38, v153
	ds_read_b128 v[186:189], v150
	ds_read_b128 v[190:193], v150 offset:1024
	ds_read_b128 v[206:209], v150 offset:2048
	ds_read_b128 v[210:213], v150 offset:3072
	v_lshl_add_u64 v[246:247], v[146:147], 0, s[68:69]
	s_add_i32 m0, s76, 0xc000
	ds_read_b128 v[214:217], v167
	ds_read_b128 v[218:221], v167 offset:1024
	ds_read_b128 v[222:225], v167 offset:2048
	ds_read_b128 v[226:229], v167 offset:3072
	ds_read_b128 v[230:233], v167 offset:4096
	ds_read_b128 v[234:237], v167 offset:5120
	ds_read_b128 v[238:241], v167 offset:6144
	ds_read_b128 v[242:245], v167 offset:7168
	global_load_lds_dwordx4 v[246:247], off
	v_lshl_add_u64 v[246:247], v[148:149], 0, s[68:69]
	s_add_i32 m0, s76, 0xe000
	s_nop 0
	global_load_lds_dwordx4 v[246:247], off
	s_waitcnt vmcnt(8)
	s_waitcnt lgkmcnt(0)
	s_setprio 1
	s_barrier
	v_mfma_f32_16x16x32_bf16 v[126:129], v[170:173], v[214:217], v[126:129]
	v_mfma_f32_16x16x32_bf16 v[122:125], v[178:181], v[214:217], v[122:125]
	v_mfma_f32_16x16x32_bf16 v[110:113], v[170:173], v[222:225], v[110:113]
	v_mfma_f32_16x16x32_bf16 v[106:109], v[178:181], v[222:225], v[106:109]
	v_mfma_f32_16x16x32_bf16 v[94:97], v[170:173], v[230:233], v[94:97]
	v_mfma_f32_16x16x32_bf16 v[90:93], v[178:181], v[230:233], v[90:93]
	v_mfma_f32_16x16x32_bf16 v[78:81], v[170:173], v[238:241], v[78:81]
	v_mfma_f32_16x16x32_bf16 v[74:77], v[178:181], v[238:241], v[74:77]
	v_mfma_f32_16x16x32_bf16 v[126:129], v[174:177], v[218:221], v[126:129]
	v_mfma_f32_16x16x32_bf16 v[122:125], v[182:185], v[218:221], v[122:125]
	v_mfma_f32_16x16x32_bf16 v[110:113], v[174:177], v[226:229], v[110:113]
	v_mfma_f32_16x16x32_bf16 v[106:109], v[182:185], v[226:229], v[106:109]
	v_mfma_f32_16x16x32_bf16 v[94:97], v[174:177], v[234:237], v[94:97]
	v_mfma_f32_16x16x32_bf16 v[90:93], v[182:185], v[234:237], v[90:93]
	v_mfma_f32_16x16x32_bf16 v[78:81], v[174:177], v[242:245], v[78:81]
	v_mfma_f32_16x16x32_bf16 v[74:77], v[182:185], v[242:245], v[74:77]
	v_mfma_f32_16x16x32_bf16 v[118:121], v[186:189], v[214:217], v[118:121]
	v_mfma_f32_16x16x32_bf16 v[114:117], v[206:209], v[214:217], v[114:117]
	v_mfma_f32_16x16x32_bf16 v[102:105], v[186:189], v[222:225], v[102:105]
	v_mfma_f32_16x16x32_bf16 v[98:101], v[206:209], v[222:225], v[98:101]
	v_mfma_f32_16x16x32_bf16 v[86:89], v[186:189], v[230:233], v[86:89]
	v_mfma_f32_16x16x32_bf16 v[82:85], v[206:209], v[230:233], v[82:85]
	v_mfma_f32_16x16x32_bf16 v[70:73], v[186:189], v[238:241], v[70:73]
	v_mfma_f32_16x16x32_bf16 v[66:69], v[206:209], v[238:241], v[66:69]
	v_mfma_f32_16x16x32_bf16 v[118:121], v[190:193], v[218:221], v[118:121]
	v_mfma_f32_16x16x32_bf16 v[114:117], v[210:213], v[218:221], v[114:117]
	v_mfma_f32_16x16x32_bf16 v[102:105], v[190:193], v[226:229], v[102:105]
	v_mfma_f32_16x16x32_bf16 v[98:101], v[210:213], v[226:229], v[98:101]
	v_mfma_f32_16x16x32_bf16 v[86:89], v[190:193], v[234:237], v[86:89]
	v_mfma_f32_16x16x32_bf16 v[82:85], v[210:213], v[234:237], v[82:85]
	s_setprio 2
	v_mfma_f32_16x16x32_bf16 v[70:73], v[190:193], v[242:245], v[70:73]
	s_barrier
	v_mfma_f32_16x16x32_bf16 v[66:69], v[210:213], v[242:245], v[66:69]
	s_setprio 0
	s_add_i32 s39, s92, s75
	v_lshl_add_u64 v[246:247], s[70:71], 0, v[0:1]
	s_mov_b32 m0, s39
	ds_read_b128 v[214:217], v167 offset:16384
	ds_read_b128 v[218:221], v167 offset:17408
	ds_read_b128 v[222:225], v167 offset:18432
	ds_read_b128 v[226:229], v167 offset:19456
	ds_read_b128 v[230:233], v167 offset:20480
	ds_read_b128 v[234:237], v167 offset:21504
	ds_read_b128 v[238:241], v167 offset:22528
	ds_read_b128 v[242:245], v167 offset:23552
	global_load_lds_dwordx4 v[246:247], off
	s_add_i32 m0, s39, 0x2000
	s_add_u32 s50, s70, 0x40000
	v_lshl_add_u64 v[248:249], s[70:71], 0, v[130:131]
	s_addc_u32 s51, s71, 0
	s_add_i32 s38, s38, s75
	global_load_lds_dwordx4 v[248:249], off
	v_lshl_add_u64 v[250:251], s[50:51], 0, v[0:1]
	s_mov_b32 m0, s38
	v_lshl_add_u64 v[252:253], s[72:73], 0, v[132:133]
	global_load_lds_dwordx4 v[250:251], off
	v_lshl_add_u64 v[250:251], s[50:51], 0, v[130:131]
	s_add_i32 m0, s38, 0x2000
	s_nop 0
	global_load_lds_dwordx4 v[250:251], off
	v_lshl_add_u64 v[250:251], s[72:73], 0, v[134:135]
	s_mov_b32 m0, s76
	s_nop 0
	global_load_lds_dwordx4 v[250:251], off
	s_mov_b32 m0, s77
	s_nop 0
	global_load_lds_dwordx4 v[252:253], off
	s_waitcnt vmcnt(8)
	s_waitcnt lgkmcnt(0)
	s_setprio 1
	s_barrier
; #define PG8_STAGE(bufoff, gbase, voff) do { _Pragma("unroll") for (int _i = 0; _i < 2; ++_i) \
;         __builtin_amdgcn_global_load_lds((const unsigned*)((const char*)(gbase) + (voff)[_i]), (PG8_LAS unsigned*)(lds + (bufoff) + ldsw + _i * 8192), 16, 0, 0); } while (0)
; #define PG8_LDA(dst, b, h) do { _Pragma("unroll") for (int m = 0; m < 4; ++m) _Pragma("unroll") for (int k = 0; k < 2; ++k) dst[m][k] = *(const PG8_LAS bf16x8*)(lds + PG8_SA(b, h) + aoff + m * 2048 + k * 1024); } while (0)
; #define PG8_LDB(dst, b, h) do { _Pragma("unroll") for (int n = 0; n < 2; ++n) _Pragma("unroll") for (int k = 0; k < 2; ++k) dst[n][k] = *(const PG8_LAS bf16x8*)(lds + PG8_SB(b, h) + boff + n * 2048 + k * 1024); } while (0)
; #define PG8_MMA(ai, bj, At, Bt) do { __builtin_amdgcn_s_setprio(1); _Pragma("unroll") for (int m = 0; m < 4; ++m) _Pragma("unroll") for (int n = 0; n < 2; ++n) _Pragma("unroll") for (int k = 0; k < 2; ++k) \
;         acc[ai][bj][m][n] = __builtin_amdgcn_mfma_f32_16x16x32_bf16(Bt[n][k], At[m][k], acc[ai][bj][m][n], 0, 0, 0); __builtin_amdgcn_s_setprio(0); } while (0)
; #define PG8_WAIT_V(n) asm volatile("s_waitcnt vmcnt(" #n ")" ::: "memory")
; #define PG8_WAIT_L(n) asm volatile("s_waitcnt lgkmcnt(" #n ")" ::: "memory")
; #define PG8_BAR __builtin_amdgcn_s_barrier()
; #define PG8_SCHED __builtin_amdgcn_sched_barrier(0)
; template <class Epi, class Sched, bool ALIGN_EPI = false, bool SP2 = false>
; __device__ __forceinline__ void gemm_phase(PG8_LAS unsigned char* lds, const Gemm g, const Sched& S, const Epi& E, const int tid) {
;     ...
;             PG8_WAIT_V(8); PG8_WAIT_L(0); PG8_BAR; PG8_MMA(1, 0, At, B0); PG8_MMA(1, 1, At, B1); PG8_BAR; PG8_SCHED;
;             PG8_LDB(B0, 1, 0); PG8_LDB(B1, 1, 1); PG8_SCHED; PG8_LDA(At, 1, 0); PG8_STAGE(PG8_SA(0, 1), a2 + hstep, voffA);
;             PG8_WAIT_V(8); PG8_WAIT_L(0); PG8_BAR; PG8_MMA(0, 0, At, B0); PG8_MMA(0, 1, At, B1); PG8_BAR; PG8_SCHED;
	v_mfma_f32_16x16x32_bf16 v[62:65], v[170:173], v[214:217], v[62:65]
	v_mfma_f32_16x16x32_bf16 v[58:61], v[178:181], v[214:217], v[58:61]
	v_mfma_f32_16x16x32_bf16 v[46:49], v[170:173], v[222:225], v[46:49]
	v_mfma_f32_16x16x32_bf16 v[42:45], v[178:181], v[222:225], v[42:45]
	v_mfma_f32_16x16x32_bf16 v[30:33], v[170:173], v[230:233], v[30:33]
	v_mfma_f32_16x16x32_bf16 v[26:29], v[178:181], v[230:233], v[26:29]
	v_mfma_f32_16x16x32_bf16 v[14:17], v[170:173], v[238:241], v[14:17]
	v_mfma_f32_16x16x32_bf16 v[10:13], v[178:181], v[238:241], v[10:13]
	v_mfma_f32_16x16x32_bf16 v[62:65], v[174:177], v[218:221], v[62:65]
	v_mfma_f32_16x16x32_bf16 v[58:61], v[182:185], v[218:221], v[58:61]
	v_mfma_f32_16x16x32_bf16 v[46:49], v[174:177], v[226:229], v[46:49]
	v_mfma_f32_16x16x32_bf16 v[42:45], v[182:185], v[226:229], v[42:45]
	v_mfma_f32_16x16x32_bf16 v[30:33], v[174:177], v[234:237], v[30:33]
	v_mfma_f32_16x16x32_bf16 v[26:29], v[182:185], v[234:237], v[26:29]
	v_mfma_f32_16x16x32_bf16 v[14:17], v[174:177], v[242:245], v[14:17]
	v_mfma_f32_16x16x32_bf16 v[10:13], v[182:185], v[242:245], v[10:13]
	v_mfma_f32_16x16x32_bf16 v[54:57], v[186:189], v[214:217], v[54:57]
	v_mfma_f32_16x16x32_bf16 v[50:53], v[206:209], v[214:217], v[50:53]
	v_mfma_f32_16x16x32_bf16 v[38:41], v[186:189], v[222:225], v[38:41]
	v_mfma_f32_16x16x32_bf16 v[34:37], v[206:209], v[222:225], v[34:37]
	v_mfma_f32_16x16x32_bf16 v[22:25], v[186:189], v[230:233], v[22:25]
	v_mfma_f32_16x16x32_bf16 v[18:21], v[206:209], v[230:233], v[18:21]
	v_mfma_f32_16x16x32_bf16 v[6:9], v[186:189], v[238:241], v[6:9]
	v_mfma_f32_16x16x32_bf16 v[2:5], v[206:209], v[238:241], v[2:5]
	v_mfma_f32_16x16x32_bf16 v[54:57], v[190:193], v[218:221], v[54:57]
	v_mfma_f32_16x16x32_bf16 v[50:53], v[210:213], v[218:221], v[50:53]
	v_mfma_f32_16x16x32_bf16 v[38:41], v[190:193], v[226:229], v[38:41]
	v_mfma_f32_16x16x32_bf16 v[34:37], v[210:213], v[226:229], v[34:37]
	v_mfma_f32_16x16x32_bf16 v[22:25], v[190:193], v[234:237], v[22:25]
	v_mfma_f32_16x16x32_bf16 v[18:21], v[210:213], v[234:237], v[18:21]
	s_setprio 2
	v_mfma_f32_16x16x32_bf16 v[6:9], v[190:193], v[242:245], v[6:9]
	s_barrier
	v_mfma_f32_16x16x32_bf16 v[2:5], v[210:213], v[242:245], v[2:5]
	s_setprio 0
	s_add_i32 s38, 0, 0x18000
	v_add_u32_e32 v150, s38, v153
	s_add_i32 s39, 0, 0x1c000
	ds_read_b128 v[170:173], v150
	ds_read_b128 v[174:177], v150 offset:1024
	ds_read_b128 v[178:181], v150 offset:2048
	ds_read_b128 v[182:185], v150 offset:3072
	v_add_u32_e32 v150, s39, v153
	ds_read_b128 v[186:189], v150
	ds_read_b128 v[190:193], v150 offset:1024
	ds_read_b128 v[206:209], v150 offset:2048
	ds_read_b128 v[210:213], v150 offset:3072
	s_add_u32 s50, s72, 0x40000
	s_addc_u32 s51, s73, 0
	s_mov_b32 m0, s78
	v_lshl_add_u64 v[194:195], s[50:51], 0, v[134:135]
	ds_read_b128 v[214:217], v167 offset:32768
	ds_read_b128 v[218:221], v167 offset:33792
	ds_read_b128 v[222:225], v167 offset:34816
	ds_read_b128 v[226:229], v167 offset:35840
	ds_read_b128 v[230:233], v167 offset:36864
	ds_read_b128 v[234:237], v167 offset:37888
	ds_read_b128 v[238:241], v167 offset:38912
	ds_read_b128 v[242:245], v167 offset:39936
	global_load_lds_dwordx4 v[194:195], off
	v_lshl_add_u64 v[194:195], s[50:51], 0, v[132:133]
	s_mov_b32 m0, s79
	s_nop 0
	global_load_lds_dwordx4 v[194:195], off
	s_waitcnt vmcnt(8)
	s_waitcnt lgkmcnt(0)
	s_setprio 1
	s_barrier
	v_mfma_f32_16x16x32_bf16 v[126:129], v[170:173], v[214:217], v[126:129]
	v_mfma_f32_16x16x32_bf16 v[122:125], v[178:181], v[214:217], v[122:125]
	v_mfma_f32_16x16x32_bf16 v[110:113], v[170:173], v[222:225], v[110:113]
	v_mfma_f32_16x16x32_bf16 v[106:109], v[178:181], v[222:225], v[106:109]
	v_mfma_f32_16x16x32_bf16 v[94:97], v[170:173], v[230:233], v[94:97]
	v_mfma_f32_16x16x32_bf16 v[90:93], v[178:181], v[230:233], v[90:93]
	v_mfma_f32_16x16x32_bf16 v[78:81], v[170:173], v[238:241], v[78:81]
	v_mfma_f32_16x16x32_bf16 v[74:77], v[178:181], v[238:241], v[74:77]
	v_mfma_f32_16x16x32_bf16 v[126:129], v[174:177], v[218:221], v[126:129]
	v_mfma_f32_16x16x32_bf16 v[122:125], v[182:185], v[218:221], v[122:125]
	v_mfma_f32_16x16x32_bf16 v[110:113], v[174:177], v[226:229], v[110:113]
	v_mfma_f32_16x16x32_bf16 v[106:109], v[182:185], v[226:229], v[106:109]
	v_mfma_f32_16x16x32_bf16 v[94:97], v[174:177], v[234:237], v[94:97]
	v_mfma_f32_16x16x32_bf16 v[90:93], v[182:185], v[234:237], v[90:93]
	v_mfma_f32_16x16x32_bf16 v[78:81], v[174:177], v[242:245], v[78:81]
	v_mfma_f32_16x16x32_bf16 v[74:77], v[182:185], v[242:245], v[74:77]
	v_mfma_f32_16x16x32_bf16 v[118:121], v[186:189], v[214:217], v[118:121]
	v_mfma_f32_16x16x32_bf16 v[114:117], v[206:209], v[214:217], v[114:117]
	v_mfma_f32_16x16x32_bf16 v[102:105], v[186:189], v[222:225], v[102:105]
	v_mfma_f32_16x16x32_bf16 v[98:101], v[206:209], v[222:225], v[98:101]
	v_mfma_f32_16x16x32_bf16 v[86:89], v[186:189], v[230:233], v[86:89]
	v_mfma_f32_16x16x32_bf16 v[82:85], v[206:209], v[230:233], v[82:85]
	v_mfma_f32_16x16x32_bf16 v[70:73], v[186:189], v[238:241], v[70:73]
	v_mfma_f32_16x16x32_bf16 v[66:69], v[206:209], v[238:241], v[66:69]
	v_mfma_f32_16x16x32_bf16 v[118:121], v[190:193], v[218:221], v[118:121]
	v_mfma_f32_16x16x32_bf16 v[114:117], v[210:213], v[218:221], v[114:117]
	v_mfma_f32_16x16x32_bf16 v[102:105], v[190:193], v[226:229], v[102:105]
	v_mfma_f32_16x16x32_bf16 v[98:101], v[210:213], v[226:229], v[98:101]
	v_mfma_f32_16x16x32_bf16 v[86:89], v[190:193], v[234:237], v[86:89]
	v_mfma_f32_16x16x32_bf16 v[82:85], v[210:213], v[234:237], v[82:85]
	s_setprio 2
	v_mfma_f32_16x16x32_bf16 v[70:73], v[190:193], v[242:245], v[70:73]
	s_barrier
; #define PG8_STAGE(bufoff, gbase, voff) do { _Pragma("unroll") for (int _i = 0; _i < 2; ++_i) \
;         __builtin_amdgcn_global_load_lds((const unsigned*)((const char*)(gbase) + (voff)[_i]), (PG8_LAS unsigned*)(lds + (bufoff) + ldsw + _i * 8192), 16, 0, 0); } while (0)
; #define PG8_LDA(dst, b, h) do { _Pragma("unroll") for (int m = 0; m < 4; ++m) _Pragma("unroll") for (int k = 0; k < 2; ++k) dst[m][k] = *(const PG8_LAS bf16x8*)(lds + PG8_SA(b, h) + aoff + m * 2048 + k * 1024); } while (0)
; #define PG8_MMA(ai, bj, At, Bt) do { __builtin_amdgcn_s_setprio(1); _Pragma("unroll") for (int m = 0; m < 4; ++m) _Pragma("unroll") for (int n = 0; n < 2; ++n) _Pragma("unroll") for (int k = 0; k < 2; ++k) \
;         acc[ai][bj][m][n] = __builtin_amdgcn_mfma_f32_16x16x32_bf16(Bt[n][k], At[m][k], acc[ai][bj][m][n], 0, 0, 0); __builtin_amdgcn_s_setprio(0); } while (0)
; #define PG8_WAIT_V(n) asm volatile("s_waitcnt vmcnt(" #n ")" ::: "memory")
; #define PG8_WAIT_L(n) asm volatile("s_waitcnt lgkmcnt(" #n ")" ::: "memory")
; #define PG8_BAR __builtin_amdgcn_s_barrier()
; #define PG8_SCHED __builtin_amdgcn_sched_barrier(0)
; template <class Epi, class Sched, bool ALIGN_EPI = false, bool SP2 = false>
; __device__ __forceinline__ void gemm_phase(PG8_LAS unsigned char* lds, const Gemm g, const Sched& S, const Epi& E, const int tid) {
;     ...
;             PG8_LDA(At, 1, 1); PG8_STAGE(PG8_SB(1, 0), b3, voffB); PG8_STAGE(PG8_SB(1, 1), b3 + hstep, voffB); PG8_STAGE(PG8_SA(1, 0), a3, voffA);
;             PG8_WAIT_V(8); PG8_WAIT_L(0); PG8_BAR; PG8_MMA(1, 0, At, B0); PG8_MMA(1, 1, At, B1); PG8_BAR; PG8_SCHED;
	v_mfma_f32_16x16x32_bf16 v[66:69], v[210:213], v[242:245], v[66:69]
	s_setprio 0
	s_add_i32 s38, s38, s75
	v_lshl_add_u64 v[194:195], v[246:247], 0, s[56:57]
	s_mov_b32 m0, s38
	ds_read_b128 v[214:217], v167 offset:49152
	ds_read_b128 v[218:221], v167 offset:50176
	ds_read_b128 v[222:225], v167 offset:51200
	ds_read_b128 v[226:229], v167 offset:52224
	ds_read_b128 v[230:233], v167 offset:53248
	ds_read_b128 v[234:237], v167 offset:54272
	ds_read_b128 v[238:241], v167 offset:55296
	ds_read_b128 v[242:245], v167 offset:56320
	global_load_lds_dwordx4 v[194:195], off
	s_add_i32 m0, s38, 0x2000
	s_add_u32 s50, s70, 0x40080
	v_lshl_add_u64 v[194:195], v[248:249], 0, s[56:57]
	s_addc_u32 s51, s71, 0
	s_add_i32 s38, s39, s75
	global_load_lds_dwordx4 v[194:195], off
	v_lshl_add_u64 v[194:195], s[50:51], 0, v[0:1]
	s_mov_b32 m0, s38
	s_nop 0
	global_load_lds_dwordx4 v[194:195], off
	v_lshl_add_u64 v[194:195], s[50:51], 0, v[130:131]
	s_add_i32 m0, s38, 0x2000
	s_nop 0
	global_load_lds_dwordx4 v[194:195], off
	v_lshl_add_u64 v[194:195], v[250:251], 0, s[56:57]
	s_mov_b32 m0, s80
	s_nop 0
	global_load_lds_dwordx4 v[194:195], off
	v_lshl_add_u64 v[194:195], v[252:253], 0, s[56:57]
	s_mov_b32 m0, s81
	s_nop 0
	global_load_lds_dwordx4 v[194:195], off
	s_waitcnt vmcnt(8)
	s_waitcnt lgkmcnt(0)
	s_setprio 1
	s_barrier
	v_mfma_f32_16x16x32_bf16 v[62:65], v[170:173], v[214:217], v[62:65]
	v_mfma_f32_16x16x32_bf16 v[58:61], v[178:181], v[214:217], v[58:61]
	v_mfma_f32_16x16x32_bf16 v[46:49], v[170:173], v[222:225], v[46:49]
	v_mfma_f32_16x16x32_bf16 v[42:45], v[178:181], v[222:225], v[42:45]
	v_mfma_f32_16x16x32_bf16 v[30:33], v[170:173], v[230:233], v[30:33]
	v_mfma_f32_16x16x32_bf16 v[26:29], v[178:181], v[230:233], v[26:29]
	v_mfma_f32_16x16x32_bf16 v[14:17], v[170:173], v[238:241], v[14:17]
	v_mfma_f32_16x16x32_bf16 v[10:13], v[178:181], v[238:241], v[10:13]
	v_mfma_f32_16x16x32_bf16 v[62:65], v[174:177], v[218:221], v[62:65]
	v_mfma_f32_16x16x32_bf16 v[58:61], v[182:185], v[218:221], v[58:61]
	v_mfma_f32_16x16x32_bf16 v[46:49], v[174:177], v[226:229], v[46:49]
	v_mfma_f32_16x16x32_bf16 v[42:45], v[182:185], v[226:229], v[42:45]
	v_mfma_f32_16x16x32_bf16 v[30:33], v[174:177], v[234:237], v[30:33]
	v_mfma_f32_16x16x32_bf16 v[26:29], v[182:185], v[234:237], v[26:29]
	v_mfma_f32_16x16x32_bf16 v[14:17], v[174:177], v[242:245], v[14:17]
	v_mfma_f32_16x16x32_bf16 v[10:13], v[182:185], v[242:245], v[10:13]
	v_mfma_f32_16x16x32_bf16 v[54:57], v[186:189], v[214:217], v[54:57]
	v_mfma_f32_16x16x32_bf16 v[50:53], v[206:209], v[214:217], v[50:53]
	v_mfma_f32_16x16x32_bf16 v[38:41], v[186:189], v[222:225], v[38:41]
	v_mfma_f32_16x16x32_bf16 v[34:37], v[206:209], v[222:225], v[34:37]
	v_mfma_f32_16x16x32_bf16 v[22:25], v[186:189], v[230:233], v[22:25]
	v_mfma_f32_16x16x32_bf16 v[18:21], v[206:209], v[230:233], v[18:21]
	v_mfma_f32_16x16x32_bf16 v[6:9], v[186:189], v[238:241], v[6:9]
	v_mfma_f32_16x16x32_bf16 v[2:5], v[206:209], v[238:241], v[2:5]
	v_mfma_f32_16x16x32_bf16 v[54:57], v[190:193], v[218:221], v[54:57]
	v_mfma_f32_16x16x32_bf16 v[50:53], v[210:213], v[218:221], v[50:53]
	v_mfma_f32_16x16x32_bf16 v[38:41], v[190:193], v[226:229], v[38:41]
	v_mfma_f32_16x16x32_bf16 v[34:37], v[210:213], v[226:229], v[34:37]
	v_mfma_f32_16x16x32_bf16 v[22:25], v[190:193], v[234:237], v[22:25]
	v_mfma_f32_16x16x32_bf16 v[18:21], v[210:213], v[234:237], v[18:21]
	s_setprio 2
	v_mfma_f32_16x16x32_bf16 v[6:9], v[190:193], v[242:245], v[6:9]
	s_barrier
	v_mfma_f32_16x16x32_bf16 v[2:5], v[210:213], v[242:245], v[2:5]
	s_setprio 0
	s_add_i32 s91, s91, 2
	s_add_u32 s68, s68, 0x100
	s_addc_u32 s69, s69, 0
	s_cmp_gt_u32 s91, 13
	s_cbranch_scc1 .LBB0_90

;     __device__ __forceinline__ void stage_rs(const Unit& u, int tid, int wid) const { stage_rs_lds(SS, rsl, u, tid, wid); }
;     __device__ __forceinline__ void stage_rs(const Unit& u, int tid, int wid) const { stage_rs_lds(SS, rsl, u, tid, wid); }
; #define PG8_STAGE(bufoff, gbase, voff) do { _Pragma("unroll") for (int _i = 0; _i < 2; ++_i) \
;         __builtin_amdgcn_global_load_lds((const unsigned*)((const char*)(gbase) + (voff)[_i]), (PG8_LAS unsigned*)(lds + (bufoff) + ldsw + _i * 8192), 16, 0, 0); } while (0)
; #define PG8_LDA(dst, b, h) do { _Pragma("unroll") for (int m = 0; m < 4; ++m) _Pragma("unroll") for (int k = 0; k < 2; ++k) dst[m][k] = *(const PG8_LAS bf16x8*)(lds + PG8_SA(b, h) + aoff + m * 2048 + k * 1024); } while (0)
; #define PG8_LDB(dst, b, h) do { _Pragma("unroll") for (int n = 0; n < 2; ++n) _Pragma("unroll") for (int k = 0; k < 2; ++k) dst[n][k] = *(const PG8_LAS bf16x8*)(lds + PG8_SB(b, h) + boff + n * 2048 + k * 1024); } while (0)
; #define PG8_BAR __builtin_amdgcn_s_barrier()
; template <class Epi, class Sched, bool ALIGN_EPI = false, bool SP2 = false>
; __device__ __forceinline__ void gemm_phase(PG8_LAS unsigned char* lds, const Gemm g, const Sched& S, const Epi& E, const int tid) {
;     ...
;         for (int t = 0; t < nt; t += 2) {
;             const bool last = (t == nt - 2);
;             if constexpr (Epi::RS_LDS) { if (t == nt - 4) E.stage_rs(cur, tid, wid); }
;             if constexpr (Epi::PREFETCH) { if (t >= nt - 8) E.prefetch(cur, lds, tid, wid, (t - (nt - 8)) >> 1); }
;             const char* a1 = cA + (size_t)(t + 1) * kstep;
;             const char* a2 = last ? nA : cA + (size_t)(t + 2) * kstep; const char* b2 = last ? nB : cB + (size_t)(t + 2) * kstep;
;             const char* a3 = a2 + kstep; const char* b3 = b2 + kstep;
;             if (last && has_next) S.a_ready(nxt);
;             if constexpr (SP2) {
;             PG8_LDB(B0, 0, 0); PG8_LDB(B1, 0, 1); PG8_SCHED; PG8_LDA(At, 0, 0); PG8_STAGE(PG8_SA(1, 1), a1 + hstep, voffA);
;             PG8_WAIT_V(8); PG8_WAIT_L(0); PG8_BAR; PG8_MMA(0, 0, At, B0); PG8_MMA(0, 1, At, B1); PG8_BAR; PG8_SCHED;
;             PG8_LDA(At, 0, 1); PG8_STAGE(PG8_SB(0, 0), b2, voffB); PG8_STAGE(PG8_SB(0, 1), b2 + hstep, voffB); PG8_STAGE(PG8_SA(0, 0), a2, voffA);
;             PG8_WAIT_V(8); PG8_WAIT_L(0); PG8_BAR; PG8_MMA(1, 0, At, B0); PG8_MMA(1, 1, At, B1); PG8_BAR; PG8_SCHED;
.LBB0_208:
	s_add_u32 s38, s10, s12
	s_addc_u32 s39, s11, s13
	s_add_u32 s38, s38, 0x100
	s_addc_u32 s39, s39, 0
	s_add_u32 s51, vcc_lo, s12
	s_addc_u32 s74, vcc_hi, s13
	s_add_i32 s59, 0, 0x10000
	s_cmpk_eq_i32 s12, 0x700
	s_cselect_b32 s77, s49, s39
	s_cselect_b32 s76, s78, s38
	v_add_u32_e32 v0, s59, v153
	s_cselect_b32 s75, s69, s74
	s_cselect_b32 s74, s79, s51
	s_add_i32 s51, 0, 0x14000
	ds_read_b128 v[170:173], v0
	ds_read_b128 v[174:177], v0 offset:1024
	ds_read_b128 v[178:181], v0 offset:2048
	ds_read_b128 v[182:185], v0 offset:3072
	v_add_u32_e32 v0, s51, v153
	ds_read_b128 v[186:189], v0
	ds_read_b128 v[190:193], v0 offset:1024
	ds_read_b128 v[206:209], v0 offset:2048
	ds_read_b128 v[210:213], v0 offset:3072
	v_lshl_add_u64 v[194:195], v[148:149], 0, s[12:13]
	s_add_i32 m0, s84, 0xc000
	ds_read_b128 v[214:217], v167
	ds_read_b128 v[218:221], v167 offset:1024
	ds_read_b128 v[222:225], v167 offset:2048
	ds_read_b128 v[226:229], v167 offset:3072
	ds_read_b128 v[230:233], v167 offset:4096
	ds_read_b128 v[234:237], v167 offset:5120
	ds_read_b128 v[238:241], v167 offset:6144
	ds_read_b128 v[242:245], v167 offset:7168
	global_load_lds_dwordx4 v[194:195], off
	v_lshl_add_u64 v[194:195], v[150:151], 0, s[12:13]
	s_add_i32 m0, s84, 0xe000
	s_nop 0
	global_load_lds_dwordx4 v[194:195], off
	s_waitcnt vmcnt(8)
	s_waitcnt lgkmcnt(0)
	s_setprio 1
	s_barrier
	v_mfma_f32_16x16x32_bf16 v[126:129], v[170:173], v[214:217], v[126:129]
	v_mfma_f32_16x16x32_bf16 v[122:125], v[178:181], v[214:217], v[122:125]
	v_mfma_f32_16x16x32_bf16 v[110:113], v[170:173], v[222:225], v[110:113]
	v_mfma_f32_16x16x32_bf16 v[106:109], v[178:181], v[222:225], v[106:109]
	v_mfma_f32_16x16x32_bf16 v[94:97], v[170:173], v[230:233], v[94:97]
	v_mfma_f32_16x16x32_bf16 v[90:93], v[178:181], v[230:233], v[90:93]
	v_mfma_f32_16x16x32_bf16 v[78:81], v[170:173], v[238:241], v[78:81]
	v_mfma_f32_16x16x32_bf16 v[74:77], v[178:181], v[238:241], v[74:77]
	v_mfma_f32_16x16x32_bf16 v[126:129], v[174:177], v[218:221], v[126:129]
	v_mfma_f32_16x16x32_bf16 v[122:125], v[182:185], v[218:221], v[122:125]
	v_mfma_f32_16x16x32_bf16 v[110:113], v[174:177], v[226:229], v[110:113]
	v_mfma_f32_16x16x32_bf16 v[106:109], v[182:185], v[226:229], v[106:109]
	v_mfma_f32_16x16x32_bf16 v[94:97], v[174:177], v[234:237], v[94:97]
	v_mfma_f32_16x16x32_bf16 v[90:93], v[182:185], v[234:237], v[90:93]
	v_mfma_f32_16x16x32_bf16 v[78:81], v[174:177], v[242:245], v[78:81]
	v_mfma_f32_16x16x32_bf16 v[74:77], v[182:185], v[242:245], v[74:77]
	v_mfma_f32_16x16x32_bf16 v[118:121], v[186:189], v[214:217], v[118:121]
	v_mfma_f32_16x16x32_bf16 v[114:117], v[206:209], v[214:217], v[114:117]
	v_mfma_f32_16x16x32_bf16 v[102:105], v[186:189], v[222:225], v[102:105]
	v_mfma_f32_16x16x32_bf16 v[98:101], v[206:209], v[222:225], v[98:101]
	v_mfma_f32_16x16x32_bf16 v[86:89], v[186:189], v[230:233], v[86:89]
	v_mfma_f32_16x16x32_bf16 v[82:85], v[206:209], v[230:233], v[82:85]
	v_mfma_f32_16x16x32_bf16 v[70:73], v[186:189], v[238:241], v[70:73]
	v_mfma_f32_16x16x32_bf16 v[66:69], v[206:209], v[238:241], v[66:69]
	v_mfma_f32_16x16x32_bf16 v[118:121], v[190:193], v[218:221], v[118:121]
	v_mfma_f32_16x16x32_bf16 v[114:117], v[210:213], v[218:221], v[114:117]
	v_mfma_f32_16x16x32_bf16 v[102:105], v[190:193], v[226:229], v[102:105]
	v_mfma_f32_16x16x32_bf16 v[98:101], v[210:213], v[226:229], v[98:101]
	v_mfma_f32_16x16x32_bf16 v[86:89], v[190:193], v[234:237], v[86:89]
	v_mfma_f32_16x16x32_bf16 v[82:85], v[210:213], v[234:237], v[82:85]
	s_setprio 2
	v_mfma_f32_16x16x32_bf16 v[70:73], v[190:193], v[242:245], v[70:73]
	s_barrier
	v_mfma_f32_16x16x32_bf16 v[66:69], v[210:213], v[242:245], v[66:69]
	s_setprio 0
	s_add_i32 s38, s59, s83
	v_lshl_add_u64 v[194:195], s[74:75], 0, v[134:135]
	s_mov_b32 m0, s38
	ds_read_b128 v[214:217], v167 offset:16384
	ds_read_b128 v[218:221], v167 offset:17408
	ds_read_b128 v[222:225], v167 offset:18432
	ds_read_b128 v[226:229], v167 offset:19456
	ds_read_b128 v[230:233], v167 offset:20480
	ds_read_b128 v[234:237], v167 offset:21504
	ds_read_b128 v[238:241], v167 offset:22528
	ds_read_b128 v[242:245], v167 offset:23552
	global_load_lds_dwordx4 v[194:195], off
	s_add_i32 m0, s38, 0x2000
	s_add_u32 s38, s74, 0x40000
	v_lshl_add_u64 v[246:247], s[74:75], 0, v[130:131]
	s_addc_u32 s39, s75, 0
	s_add_i32 s51, s51, s83
	global_load_lds_dwordx4 v[246:247], off
	v_lshl_add_u64 v[248:249], s[38:39], 0, v[134:135]
	s_mov_b32 m0, s51
	v_lshl_add_u64 v[250:251], s[76:77], 0, v[132:133]
	global_load_lds_dwordx4 v[248:249], off
	v_lshl_add_u64 v[248:249], s[38:39], 0, v[130:131]
	s_add_i32 m0, s51, 0x2000
	s_nop 0
	global_load_lds_dwordx4 v[248:249], off
	v_lshl_add_u64 v[248:249], s[76:77], 0, v[136:137]
	s_mov_b32 m0, s84
	s_nop 0
	global_load_lds_dwordx4 v[248:249], off
	s_mov_b32 m0, s85
	s_nop 0
	global_load_lds_dwordx4 v[250:251], off
	s_waitcnt vmcnt(8)
	s_waitcnt lgkmcnt(0)
	s_setprio 1
	s_barrier
; #define PG8_STAGE(bufoff, gbase, voff) do { _Pragma("unroll") for (int _i = 0; _i < 2; ++_i) \
;         __builtin_amdgcn_global_load_lds((const unsigned*)((const char*)(gbase) + (voff)[_i]), (PG8_LAS unsigned*)(lds + (bufoff) + ldsw + _i * 8192), 16, 0, 0); } while (0)
; #define PG8_LDA(dst, b, h) do { _Pragma("unroll") for (int m = 0; m < 4; ++m) _Pragma("unroll") for (int k = 0; k < 2; ++k) dst[m][k] = *(const PG8_LAS bf16x8*)(lds + PG8_SA(b, h) + aoff + m * 2048 + k * 1024); } while (0)
; #define PG8_LDB(dst, b, h) do { _Pragma("unroll") for (int n = 0; n < 2; ++n) _Pragma("unroll") for (int k = 0; k < 2; ++k) dst[n][k] = *(const PG8_LAS bf16x8*)(lds + PG8_SB(b, h) + boff + n * 2048 + k * 1024); } while (0)
; #define PG8_MMA(ai, bj, At, Bt) do { __builtin_amdgcn_s_setprio(1); _Pragma("unroll") for (int m = 0; m < 4; ++m) _Pragma("unroll") for (int n = 0; n < 2; ++n) _Pragma("unroll") for (int k = 0; k < 2; ++k) \
;         acc[ai][bj][m][n] = __builtin_amdgcn_mfma_f32_16x16x32_bf16(Bt[n][k], At[m][k], acc[ai][bj][m][n], 0, 0, 0); __builtin_amdgcn_s_setprio(0); } while (0)
; #define PG8_WAIT_V(n) asm volatile("s_waitcnt vmcnt(" #n ")" ::: "memory")
; #define PG8_WAIT_L(n) asm volatile("s_waitcnt lgkmcnt(" #n ")" ::: "memory")
; #define PG8_BAR __builtin_amdgcn_s_barrier()
; #define PG8_SCHED __builtin_amdgcn_sched_barrier(0)
; template <class Epi, class Sched, bool ALIGN_EPI = false, bool SP2 = false>
; __device__ __forceinline__ void gemm_phase(PG8_LAS unsigned char* lds, const Gemm g, const Sched& S, const Epi& E, const int tid) {
;     ...
;             PG8_WAIT_V(8); PG8_WAIT_L(0); PG8_BAR; PG8_MMA(1, 0, At, B0); PG8_MMA(1, 1, At, B1); PG8_BAR; PG8_SCHED;
;             PG8_LDB(B0, 1, 0); PG8_LDB(B1, 1, 1); PG8_SCHED; PG8_LDA(At, 1, 0); PG8_STAGE(PG8_SA(0, 1), a2 + hstep, voffA);
;             PG8_WAIT_V(8); PG8_WAIT_L(0); PG8_BAR; PG8_MMA(0, 0, At, B0); PG8_MMA(0, 1, At, B1); PG8_BAR; PG8_SCHED;
	v_mfma_f32_16x16x32_bf16 v[62:65], v[170:173], v[214:217], v[62:65]
	v_mfma_f32_16x16x32_bf16 v[58:61], v[178:181], v[214:217], v[58:61]
	v_mfma_f32_16x16x32_bf16 v[46:49], v[170:173], v[222:225], v[46:49]
	v_mfma_f32_16x16x32_bf16 v[42:45], v[178:181], v[222:225], v[42:45]
	v_mfma_f32_16x16x32_bf16 v[30:33], v[170:173], v[230:233], v[30:33]
	v_mfma_f32_16x16x32_bf16 v[26:29], v[178:181], v[230:233], v[26:29]
	v_mfma_f32_16x16x32_bf16 v[14:17], v[170:173], v[238:241], v[14:17]
	v_mfma_f32_16x16x32_bf16 v[10:13], v[178:181], v[238:241], v[10:13]
	v_mfma_f32_16x16x32_bf16 v[62:65], v[174:177], v[218:221], v[62:65]
	v_mfma_f32_16x16x32_bf16 v[58:61], v[182:185], v[218:221], v[58:61]
	v_mfma_f32_16x16x32_bf16 v[46:49], v[174:177], v[226:229], v[46:49]
	v_mfma_f32_16x16x32_bf16 v[42:45], v[182:185], v[226:229], v[42:45]
	v_mfma_f32_16x16x32_bf16 v[30:33], v[174:177], v[234:237], v[30:33]
	v_mfma_f32_16x16x32_bf16 v[26:29], v[182:185], v[234:237], v[26:29]
	v_mfma_f32_16x16x32_bf16 v[14:17], v[174:177], v[242:245], v[14:17]
	v_mfma_f32_16x16x32_bf16 v[10:13], v[182:185], v[242:245], v[10:13]
	v_mfma_f32_16x16x32_bf16 v[54:57], v[186:189], v[214:217], v[54:57]
	v_mfma_f32_16x16x32_bf16 v[50:53], v[206:209], v[214:217], v[50:53]
	v_mfma_f32_16x16x32_bf16 v[38:41], v[186:189], v[222:225], v[38:41]
	v_mfma_f32_16x16x32_bf16 v[34:37], v[206:209], v[222:225], v[34:37]
	v_mfma_f32_16x16x32_bf16 v[22:25], v[186:189], v[230:233], v[22:25]
	v_mfma_f32_16x16x32_bf16 v[18:21], v[206:209], v[230:233], v[18:21]
	v_mfma_f32_16x16x32_bf16 v[6:9], v[186:189], v[238:241], v[6:9]
	v_mfma_f32_16x16x32_bf16 v[2:5], v[206:209], v[238:241], v[2:5]
	v_mfma_f32_16x16x32_bf16 v[54:57], v[190:193], v[218:221], v[54:57]
	v_mfma_f32_16x16x32_bf16 v[50:53], v[210:213], v[218:221], v[50:53]
	v_mfma_f32_16x16x32_bf16 v[38:41], v[190:193], v[226:229], v[38:41]
	v_mfma_f32_16x16x32_bf16 v[34:37], v[210:213], v[226:229], v[34:37]
	v_mfma_f32_16x16x32_bf16 v[22:25], v[190:193], v[234:237], v[22:25]
	v_mfma_f32_16x16x32_bf16 v[18:21], v[210:213], v[234:237], v[18:21]
	s_setprio 2
	v_mfma_f32_16x16x32_bf16 v[6:9], v[190:193], v[242:245], v[6:9]
	s_barrier
	v_mfma_f32_16x16x32_bf16 v[2:5], v[210:213], v[242:245], v[2:5]
	s_setprio 0
	s_add_i32 s51, 0, 0x18000
	v_add_u32_e32 v0, s51, v153
	s_add_i32 s59, 0, 0x1c000
	ds_read_b128 v[170:173], v0
	ds_read_b128 v[174:177], v0 offset:1024
	ds_read_b128 v[178:181], v0 offset:2048
	ds_read_b128 v[182:185], v0 offset:3072
	v_add_u32_e32 v0, s59, v153
	ds_read_b128 v[186:189], v0
	ds_read_b128 v[190:193], v0 offset:1024
	ds_read_b128 v[206:209], v0 offset:2048
	ds_read_b128 v[210:213], v0 offset:3072
	s_add_u32 s38, s76, 0x40000
	s_addc_u32 s39, s77, 0
	s_mov_b32 m0, s86
	v_lshl_add_u64 v[252:253], s[38:39], 0, v[136:137]
	ds_read_b128 v[214:217], v167 offset:32768
	ds_read_b128 v[218:221], v167 offset:33792
	ds_read_b128 v[222:225], v167 offset:34816
	ds_read_b128 v[226:229], v167 offset:35840
	ds_read_b128 v[230:233], v167 offset:36864
	ds_read_b128 v[234:237], v167 offset:37888
	ds_read_b128 v[238:241], v167 offset:38912
	ds_read_b128 v[242:245], v167 offset:39936
	global_load_lds_dwordx4 v[252:253], off
	v_lshl_add_u64 v[252:253], s[38:39], 0, v[132:133]
	s_mov_b32 m0, s87
	s_nop 0
	global_load_lds_dwordx4 v[252:253], off
	s_waitcnt vmcnt(8)
	s_waitcnt lgkmcnt(0)
	s_setprio 1
	s_barrier
	v_mfma_f32_16x16x32_bf16 v[126:129], v[170:173], v[214:217], v[126:129]
	v_mfma_f32_16x16x32_bf16 v[122:125], v[178:181], v[214:217], v[122:125]
	v_mfma_f32_16x16x32_bf16 v[110:113], v[170:173], v[222:225], v[110:113]
	v_mfma_f32_16x16x32_bf16 v[106:109], v[178:181], v[222:225], v[106:109]
	v_mfma_f32_16x16x32_bf16 v[94:97], v[170:173], v[230:233], v[94:97]
	v_mfma_f32_16x16x32_bf16 v[90:93], v[178:181], v[230:233], v[90:93]
	v_mfma_f32_16x16x32_bf16 v[78:81], v[170:173], v[238:241], v[78:81]
	v_mfma_f32_16x16x32_bf16 v[74:77], v[178:181], v[238:241], v[74:77]
	v_mfma_f32_16x16x32_bf16 v[126:129], v[174:177], v[218:221], v[126:129]
	v_mfma_f32_16x16x32_bf16 v[122:125], v[182:185], v[218:221], v[122:125]
	v_mfma_f32_16x16x32_bf16 v[110:113], v[174:177], v[226:229], v[110:113]
	v_mfma_f32_16x16x32_bf16 v[106:109], v[182:185], v[226:229], v[106:109]
	v_mfma_f32_16x16x32_bf16 v[94:97], v[174:177], v[234:237], v[94:97]
	v_mfma_f32_16x16x32_bf16 v[90:93], v[182:185], v[234:237], v[90:93]
	v_mfma_f32_16x16x32_bf16 v[78:81], v[174:177], v[242:245], v[78:81]
	v_mfma_f32_16x16x32_bf16 v[74:77], v[182:185], v[242:245], v[74:77]
	v_mfma_f32_16x16x32_bf16 v[118:121], v[186:189], v[214:217], v[118:121]
	v_mfma_f32_16x16x32_bf16 v[114:117], v[206:209], v[214:217], v[114:117]
	v_mfma_f32_16x16x32_bf16 v[102:105], v[186:189], v[222:225], v[102:105]
	v_mfma_f32_16x16x32_bf16 v[98:101], v[206:209], v[222:225], v[98:101]
	v_mfma_f32_16x16x32_bf16 v[86:89], v[186:189], v[230:233], v[86:89]
	v_mfma_f32_16x16x32_bf16 v[82:85], v[206:209], v[230:233], v[82:85]
	v_mfma_f32_16x16x32_bf16 v[70:73], v[186:189], v[238:241], v[70:73]
	v_mfma_f32_16x16x32_bf16 v[66:69], v[206:209], v[238:241], v[66:69]
	v_mfma_f32_16x16x32_bf16 v[118:121], v[190:193], v[218:221], v[118:121]
	v_mfma_f32_16x16x32_bf16 v[114:117], v[210:213], v[218:221], v[114:117]
	v_mfma_f32_16x16x32_bf16 v[102:105], v[190:193], v[226:229], v[102:105]
	v_mfma_f32_16x16x32_bf16 v[98:101], v[210:213], v[226:229], v[98:101]
	v_mfma_f32_16x16x32_bf16 v[86:89], v[190:193], v[234:237], v[86:89]
	v_mfma_f32_16x16x32_bf16 v[82:85], v[210:213], v[234:237], v[82:85]
	s_setprio 2
	v_mfma_f32_16x16x32_bf16 v[70:73], v[190:193], v[242:245], v[70:73]
	s_barrier
; #define PG8_STAGE(bufoff, gbase, voff) do { _Pragma("unroll") for (int _i = 0; _i < 2; ++_i) \
;         __builtin_amdgcn_global_load_lds((const unsigned*)((const char*)(gbase) + (voff)[_i]), (PG8_LAS unsigned*)(lds + (bufoff) + ldsw + _i * 8192), 16, 0, 0); } while (0)
; #define PG8_LDA(dst, b, h) do { _Pragma("unroll") for (int m = 0; m < 4; ++m) _Pragma("unroll") for (int k = 0; k < 2; ++k) dst[m][k] = *(const PG8_LAS bf16x8*)(lds + PG8_SA(b, h) + aoff + m * 2048 + k * 1024); } while (0)
; #define PG8_MMA(ai, bj, At, Bt) do { __builtin_amdgcn_s_setprio(1); _Pragma("unroll") for (int m = 0; m < 4; ++m) _Pragma("unroll") for (int n = 0; n < 2; ++n) _Pragma("unroll") for (int k = 0; k < 2; ++k) \
;         acc[ai][bj][m][n] = __builtin_amdgcn_mfma_f32_16x16x32_bf16(Bt[n][k], At[m][k], acc[ai][bj][m][n], 0, 0, 0); __builtin_amdgcn_s_setprio(0); } while (0)
; #define PG8_WAIT_V(n) asm volatile("s_waitcnt vmcnt(" #n ")" ::: "memory")
; #define PG8_WAIT_L(n) asm volatile("s_waitcnt lgkmcnt(" #n ")" ::: "memory")
; #define PG8_BAR __builtin_amdgcn_s_barrier()
; #define PG8_SCHED __builtin_amdgcn_sched_barrier(0)
; template <class Epi, class Sched, bool ALIGN_EPI = false, bool SP2 = false>
; __device__ __forceinline__ void gemm_phase(PG8_LAS unsigned char* lds, const Gemm g, const Sched& S, const Epi& E, const int tid) {
;     ...
;             PG8_LDA(At, 1, 1); PG8_STAGE(PG8_SB(1, 0), b3, voffB); PG8_STAGE(PG8_SB(1, 1), b3 + hstep, voffB); PG8_STAGE(PG8_SA(1, 0), a3, voffA);
;             PG8_WAIT_V(8); PG8_WAIT_L(0); PG8_BAR; PG8_MMA(1, 0, At, B0); PG8_MMA(1, 1, At, B1); PG8_BAR; PG8_SCHED;
	v_mfma_f32_16x16x32_bf16 v[66:69], v[210:213], v[242:245], v[66:69]
	s_setprio 0
	s_add_i32 s38, s51, s83
	v_lshl_add_u64 v[194:195], v[194:195], 0, s[56:57]
	s_mov_b32 m0, s38
	ds_read_b128 v[214:217], v167 offset:49152
	ds_read_b128 v[218:221], v167 offset:50176
	ds_read_b128 v[222:225], v167 offset:51200
	ds_read_b128 v[226:229], v167 offset:52224
	ds_read_b128 v[230:233], v167 offset:53248
	ds_read_b128 v[234:237], v167 offset:54272
	ds_read_b128 v[238:241], v167 offset:55296
	ds_read_b128 v[242:245], v167 offset:56320
	global_load_lds_dwordx4 v[194:195], off
	s_add_i32 m0, s38, 0x2000
	s_add_u32 s38, s74, 0x40080
	v_lshl_add_u64 v[194:195], v[246:247], 0, s[56:57]
	s_addc_u32 s39, s75, 0
	s_add_i32 s51, s59, s83
	global_load_lds_dwordx4 v[194:195], off
	v_lshl_add_u64 v[194:195], s[38:39], 0, v[134:135]
	s_mov_b32 m0, s51
	s_nop 0
	global_load_lds_dwordx4 v[194:195], off
	v_lshl_add_u64 v[194:195], s[38:39], 0, v[130:131]
	s_add_i32 m0, s51, 0x2000
	s_nop 0
	global_load_lds_dwordx4 v[194:195], off
	v_lshl_add_u64 v[194:195], v[248:249], 0, s[56:57]
	s_mov_b32 m0, s88
	s_nop 0
	global_load_lds_dwordx4 v[194:195], off
	v_lshl_add_u64 v[194:195], v[250:251], 0, s[56:57]
	s_mov_b32 m0, s89
	s_nop 0
	global_load_lds_dwordx4 v[194:195], off
	s_waitcnt vmcnt(8)
	s_waitcnt lgkmcnt(0)
	s_setprio 1
	s_barrier
	v_mfma_f32_16x16x32_bf16 v[62:65], v[170:173], v[214:217], v[62:65]
	v_mfma_f32_16x16x32_bf16 v[58:61], v[178:181], v[214:217], v[58:61]
	v_mfma_f32_16x16x32_bf16 v[46:49], v[170:173], v[222:225], v[46:49]
	v_mfma_f32_16x16x32_bf16 v[42:45], v[178:181], v[222:225], v[42:45]
	v_mfma_f32_16x16x32_bf16 v[30:33], v[170:173], v[230:233], v[30:33]
	v_mfma_f32_16x16x32_bf16 v[26:29], v[178:181], v[230:233], v[26:29]
	v_mfma_f32_16x16x32_bf16 v[14:17], v[170:173], v[238:241], v[14:17]
	v_mfma_f32_16x16x32_bf16 v[10:13], v[178:181], v[238:241], v[10:13]
	v_mfma_f32_16x16x32_bf16 v[62:65], v[174:177], v[218:221], v[62:65]
	v_mfma_f32_16x16x32_bf16 v[58:61], v[182:185], v[218:221], v[58:61]
	v_mfma_f32_16x16x32_bf16 v[46:49], v[174:177], v[226:229], v[46:49]
	v_mfma_f32_16x16x32_bf16 v[42:45], v[182:185], v[226:229], v[42:45]
	v_mfma_f32_16x16x32_bf16 v[30:33], v[174:177], v[234:237], v[30:33]
	v_mfma_f32_16x16x32_bf16 v[26:29], v[182:185], v[234:237], v[26:29]
	v_mfma_f32_16x16x32_bf16 v[14:17], v[174:177], v[242:245], v[14:17]
	v_mfma_f32_16x16x32_bf16 v[10:13], v[182:185], v[242:245], v[10:13]
	v_mfma_f32_16x16x32_bf16 v[54:57], v[186:189], v[214:217], v[54:57]
	v_mfma_f32_16x16x32_bf16 v[50:53], v[206:209], v[214:217], v[50:53]
	v_mfma_f32_16x16x32_bf16 v[38:41], v[186:189], v[222:225], v[38:41]
	v_mfma_f32_16x16x32_bf16 v[34:37], v[206:209], v[222:225], v[34:37]
	v_mfma_f32_16x16x32_bf16 v[22:25], v[186:189], v[230:233], v[22:25]
	v_mfma_f32_16x16x32_bf16 v[18:21], v[206:209], v[230:233], v[18:21]
	v_mfma_f32_16x16x32_bf16 v[6:9], v[186:189], v[238:241], v[6:9]
	v_mfma_f32_16x16x32_bf16 v[2:5], v[206:209], v[238:241], v[2:5]
	v_mfma_f32_16x16x32_bf16 v[54:57], v[190:193], v[218:221], v[54:57]
	v_mfma_f32_16x16x32_bf16 v[50:53], v[210:213], v[218:221], v[50:53]
	v_mfma_f32_16x16x32_bf16 v[38:41], v[190:193], v[226:229], v[38:41]
	v_mfma_f32_16x16x32_bf16 v[34:37], v[210:213], v[226:229], v[34:37]
	v_mfma_f32_16x16x32_bf16 v[22:25], v[190:193], v[234:237], v[22:25]
	v_mfma_f32_16x16x32_bf16 v[18:21], v[210:213], v[234:237], v[18:21]
	s_setprio 2
	v_mfma_f32_16x16x32_bf16 v[6:9], v[190:193], v[242:245], v[6:9]
	s_barrier
	v_mfma_f32_16x16x32_bf16 v[2:5], v[210:213], v[242:245], v[2:5]
	s_setprio 0
	s_add_i32 s50, s50, 2
	s_add_u32 s12, s12, 0x100
	s_addc_u32 s13, s13, 0
	s_cmp_gt_u32 s50, 13
	s_cbranch_scc1 .LBB0_211

;     __device__ __forceinline__ void stage_rs(const Unit& u, int tid, int wid) const { stage_rs_lds(SS, rsl, u, tid, wid); }
;     __device__ __forceinline__ void stage_rs(const Unit& u, int tid, int wid) const { stage_rs_lds(SS, rsl, u, tid, wid); }
; #define PG8_STAGE(bufoff, gbase, voff) do { _Pragma("unroll") for (int _i = 0; _i < 2; ++_i) \
;         __builtin_amdgcn_global_load_lds((const unsigned*)((const char*)(gbase) + (voff)[_i]), (PG8_LAS unsigned*)(lds + (bufoff) + ldsw + _i * 8192), 16, 0, 0); } while (0)
; #define PG8_LDA(dst, b, h) do { _Pragma("unroll") for (int m = 0; m < 4; ++m) _Pragma("unroll") for (int k = 0; k < 2; ++k) dst[m][k] = *(const PG8_LAS bf16x8*)(lds + PG8_SA(b, h) + aoff + m * 2048 + k * 1024); } while (0)
; #define PG8_LDB(dst, b, h) do { _Pragma("unroll") for (int n = 0; n < 2; ++n) _Pragma("unroll") for (int k = 0; k < 2; ++k) dst[n][k] = *(const PG8_LAS bf16x8*)(lds + PG8_SB(b, h) + boff + n * 2048 + k * 1024); } while (0)
; #define PG8_BAR __builtin_amdgcn_s_barrier()
; template <class Epi, class Sched, bool ALIGN_EPI = false, bool SP2 = false>
; __device__ __forceinline__ void gemm_phase(PG8_LAS unsigned char* lds, const Gemm g, const Sched& S, const Epi& E, const int tid) {
;     ...
;         for (int t = 0; t < nt; t += 2) {
;             const bool last = (t == nt - 2);
;             if constexpr (Epi::RS_LDS) { if (t == nt - 4) E.stage_rs(cur, tid, wid); }
;             if constexpr (Epi::PREFETCH) { if (t >= nt - 8) E.prefetch(cur, lds, tid, wid, (t - (nt - 8)) >> 1); }
;             const char* a1 = cA + (size_t)(t + 1) * kstep;
;             const char* a2 = last ? nA : cA + (size_t)(t + 2) * kstep; const char* b2 = last ? nB : cB + (size_t)(t + 2) * kstep;
;             const char* a3 = a2 + kstep; const char* b3 = b2 + kstep;
;             if (last && has_next) S.a_ready(nxt);
;             if constexpr (SP2) {
;             PG8_LDB(B0, 0, 0); PG8_LDB(B1, 0, 1); PG8_SCHED; PG8_LDA(At, 0, 0); PG8_STAGE(PG8_SA(1, 1), a1 + hstep, voffA);
;             PG8_WAIT_V(8); PG8_WAIT_L(0); PG8_BAR; PG8_MMA(0, 0, At, B0); PG8_MMA(0, 1, At, B1); PG8_BAR; PG8_SCHED;
;             PG8_LDA(At, 0, 1); PG8_STAGE(PG8_SB(0, 0), b2, voffB); PG8_STAGE(PG8_SB(0, 1), b2 + hstep, voffB); PG8_STAGE(PG8_SA(0, 0), a2, voffA);
;             PG8_WAIT_V(8); PG8_WAIT_L(0); PG8_BAR; PG8_MMA(1, 0, At, B0); PG8_MMA(1, 1, At, B1); PG8_BAR; PG8_SCHED;
.LBB0_618:
	s_add_i32 s85, s70, 2
	s_add_u32 s38, s68, 0x80
	s_addc_u32 s39, s69, 0
	s_add_i32 s59, 0, 0x10000
	s_cmp_eq_u32 s81, s70
	s_cselect_b32 s71, s11, s39
	s_cselect_b32 s70, s10, s38
	s_cselect_b32 s39, s67, s51
	s_cselect_b32 s38, s66, s50
	s_add_i32 s86, 0, 0x14000
	v_add_u32_e32 v142, s59, v205
	v_add_u32_e32 v180, s86, v205
	ds_read_b128 v[130:133], v142
	ds_read_b128 v[134:137], v142 offset:1024
	ds_read_b128 v[138:141], v142 offset:2048
	ds_read_b128 v[142:145], v142 offset:3072
	ds_read_b128 v[146:149], v180
	ds_read_b128 v[150:153], v180 offset:1024
	ds_read_b128 v[176:179], v180 offset:2048
	ds_read_b128 v[180:183], v180 offset:3072
	v_lshl_add_u64 v[192:193], s[68:69], 0, v[172:173]
	s_add_i32 m0, s73, 0xc000
	ds_read_b128 v[184:187], v207
	ds_read_b128 v[188:191], v207 offset:1024
	ds_read_b128 v[208:211], v207 offset:2048
	ds_read_b128 v[212:215], v207 offset:3072
	ds_read_b128 v[216:219], v207 offset:4096
	ds_read_b128 v[220:223], v207 offset:5120
	ds_read_b128 v[224:227], v207 offset:6144
	ds_read_b128 v[228:231], v207 offset:7168
	global_load_lds_dwordx4 v[192:193], off
	v_lshl_add_u64 v[192:193], s[68:69], 0, v[174:175]
	s_add_i32 m0, s73, 0xe000
	s_nop 0
	global_load_lds_dwordx4 v[192:193], off
	s_waitcnt vmcnt(8)
	s_waitcnt lgkmcnt(0)
	s_setprio 1
	s_barrier
	v_mfma_f32_16x16x32_bf16 v[126:129], v[130:133], v[184:187], v[126:129]
	v_mfma_f32_16x16x32_bf16 v[122:125], v[138:141], v[184:187], v[122:125]
	v_mfma_f32_16x16x32_bf16 v[110:113], v[130:133], v[208:211], v[110:113]
	v_mfma_f32_16x16x32_bf16 v[106:109], v[138:141], v[208:211], v[106:109]
	v_mfma_f32_16x16x32_bf16 v[94:97], v[130:133], v[216:219], v[94:97]
	v_mfma_f32_16x16x32_bf16 v[90:93], v[138:141], v[216:219], v[90:93]
	v_mfma_f32_16x16x32_bf16 v[78:81], v[130:133], v[224:227], v[78:81]
	v_mfma_f32_16x16x32_bf16 v[74:77], v[138:141], v[224:227], v[74:77]
	v_mfma_f32_16x16x32_bf16 v[126:129], v[134:137], v[188:191], v[126:129]
	v_mfma_f32_16x16x32_bf16 v[122:125], v[142:145], v[188:191], v[122:125]
	v_mfma_f32_16x16x32_bf16 v[110:113], v[134:137], v[212:215], v[110:113]
	v_mfma_f32_16x16x32_bf16 v[106:109], v[142:145], v[212:215], v[106:109]
	v_mfma_f32_16x16x32_bf16 v[94:97], v[134:137], v[220:223], v[94:97]
	v_mfma_f32_16x16x32_bf16 v[90:93], v[142:145], v[220:223], v[90:93]
	v_mfma_f32_16x16x32_bf16 v[78:81], v[134:137], v[228:231], v[78:81]
	v_mfma_f32_16x16x32_bf16 v[74:77], v[142:145], v[228:231], v[74:77]
	v_mfma_f32_16x16x32_bf16 v[118:121], v[146:149], v[184:187], v[118:121]
	v_mfma_f32_16x16x32_bf16 v[114:117], v[176:179], v[184:187], v[114:117]
	v_mfma_f32_16x16x32_bf16 v[102:105], v[146:149], v[208:211], v[102:105]
	v_mfma_f32_16x16x32_bf16 v[98:101], v[176:179], v[208:211], v[98:101]
	v_mfma_f32_16x16x32_bf16 v[86:89], v[146:149], v[216:219], v[86:89]
	v_mfma_f32_16x16x32_bf16 v[82:85], v[176:179], v[216:219], v[82:85]
	v_mfma_f32_16x16x32_bf16 v[70:73], v[146:149], v[224:227], v[70:73]
	v_mfma_f32_16x16x32_bf16 v[66:69], v[176:179], v[224:227], v[66:69]
	v_mfma_f32_16x16x32_bf16 v[118:121], v[150:153], v[188:191], v[118:121]
	v_mfma_f32_16x16x32_bf16 v[114:117], v[180:183], v[188:191], v[114:117]
	v_mfma_f32_16x16x32_bf16 v[102:105], v[150:153], v[212:215], v[102:105]
	v_mfma_f32_16x16x32_bf16 v[98:101], v[180:183], v[212:215], v[98:101]
	v_mfma_f32_16x16x32_bf16 v[86:89], v[150:153], v[220:223], v[86:89]
	v_mfma_f32_16x16x32_bf16 v[82:85], v[180:183], v[220:223], v[82:85]
	s_setprio 2
	v_mfma_f32_16x16x32_bf16 v[70:73], v[150:153], v[228:231], v[70:73]
	s_barrier
	v_mfma_f32_16x16x32_bf16 v[66:69], v[180:183], v[228:231], v[66:69]
	s_setprio 0
	s_add_i32 s59, s59, s72
	v_lshl_add_u64 v[192:193], s[38:39], 0, v[0:1]
	s_mov_b32 m0, s59
	ds_read_b128 v[184:187], v207 offset:16384
	ds_read_b128 v[188:191], v207 offset:17408
	ds_read_b128 v[208:211], v207 offset:18432
	ds_read_b128 v[212:215], v207 offset:19456
	ds_read_b128 v[216:219], v207 offset:20480
	ds_read_b128 v[220:223], v207 offset:21504
	ds_read_b128 v[224:227], v207 offset:22528
	ds_read_b128 v[228:231], v207 offset:23552
	global_load_lds_dwordx4 v[192:193], off
	s_add_i32 m0, s59, 0x2000
	v_lshl_add_u64 v[194:195], s[38:39], 0, v[166:167]
	s_add_u32 s38, s38, s14
	s_addc_u32 s39, s39, 0
	s_add_i32 s59, s86, s72
	global_load_lds_dwordx4 v[194:195], off
	v_lshl_add_u64 v[232:233], s[38:39], 0, v[0:1]
	s_mov_b32 m0, s59
	v_lshl_add_u64 v[234:235], s[38:39], 0, v[166:167]
	global_load_lds_dwordx4 v[232:233], off
	s_add_i32 m0, s59, 0x2000
	v_lshl_add_u64 v[236:237], s[70:71], 0, v[170:171]
	global_load_lds_dwordx4 v[234:235], off
	s_mov_b32 m0, s73
	v_lshl_add_u64 v[238:239], s[70:71], 0, v[168:169]
	global_load_lds_dwordx4 v[236:237], off
	s_mov_b32 m0, s74
	s_nop 0
	global_load_lds_dwordx4 v[238:239], off
	s_waitcnt vmcnt(8)
	s_waitcnt lgkmcnt(0)
	s_setprio 1
	s_barrier
; #define PG8_STAGE(bufoff, gbase, voff) do { _Pragma("unroll") for (int _i = 0; _i < 2; ++_i) \
;         __builtin_amdgcn_global_load_lds((const unsigned*)((const char*)(gbase) + (voff)[_i]), (PG8_LAS unsigned*)(lds + (bufoff) + ldsw + _i * 8192), 16, 0, 0); } while (0)
; #define PG8_LDA(dst, b, h) do { _Pragma("unroll") for (int m = 0; m < 4; ++m) _Pragma("unroll") for (int k = 0; k < 2; ++k) dst[m][k] = *(const PG8_LAS bf16x8*)(lds + PG8_SA(b, h) + aoff + m * 2048 + k * 1024); } while (0)
; #define PG8_LDB(dst, b, h) do { _Pragma("unroll") for (int n = 0; n < 2; ++n) _Pragma("unroll") for (int k = 0; k < 2; ++k) dst[n][k] = *(const PG8_LAS bf16x8*)(lds + PG8_SB(b, h) + boff + n * 2048 + k * 1024); } while (0)
; #define PG8_MMA(ai, bj, At, Bt) do { __builtin_amdgcn_s_setprio(1); _Pragma("unroll") for (int m = 0; m < 4; ++m) _Pragma("unroll") for (int n = 0; n < 2; ++n) _Pragma("unroll") for (int k = 0; k < 2; ++k) \
;         acc[ai][bj][m][n] = __builtin_amdgcn_mfma_f32_16x16x32_bf16(Bt[n][k], At[m][k], acc[ai][bj][m][n], 0, 0, 0); __builtin_amdgcn_s_setprio(0); } while (0)
; #define PG8_WAIT_V(n) asm volatile("s_waitcnt vmcnt(" #n ")" ::: "memory")
; #define PG8_WAIT_L(n) asm volatile("s_waitcnt lgkmcnt(" #n ")" ::: "memory")
; #define PG8_BAR __builtin_amdgcn_s_barrier()
; #define PG8_SCHED __builtin_amdgcn_sched_barrier(0)
; template <class Epi, class Sched, bool ALIGN_EPI = false, bool SP2 = false>
; __device__ __forceinline__ void gemm_phase(PG8_LAS unsigned char* lds, const Gemm g, const Sched& S, const Epi& E, const int tid) {
;     ...
;             PG8_WAIT_V(8); PG8_WAIT_L(0); PG8_BAR; PG8_MMA(1, 0, At, B0); PG8_MMA(1, 1, At, B1); PG8_BAR; PG8_SCHED;
;             PG8_LDB(B0, 1, 0); PG8_LDB(B1, 1, 1); PG8_SCHED; PG8_LDA(At, 1, 0); PG8_STAGE(PG8_SA(0, 1), a2 + hstep, voffA);
;             PG8_WAIT_V(8); PG8_WAIT_L(0); PG8_BAR; PG8_MMA(0, 0, At, B0); PG8_MMA(0, 1, At, B1); PG8_BAR; PG8_SCHED;
	v_mfma_f32_16x16x32_bf16 v[62:65], v[130:133], v[184:187], v[62:65]
	v_mfma_f32_16x16x32_bf16 v[58:61], v[138:141], v[184:187], v[58:61]
	v_mfma_f32_16x16x32_bf16 v[46:49], v[130:133], v[208:211], v[46:49]
	v_mfma_f32_16x16x32_bf16 v[42:45], v[138:141], v[208:211], v[42:45]
	v_mfma_f32_16x16x32_bf16 v[30:33], v[130:133], v[216:219], v[30:33]
	v_mfma_f32_16x16x32_bf16 v[26:29], v[138:141], v[216:219], v[26:29]
	v_mfma_f32_16x16x32_bf16 v[14:17], v[130:133], v[224:227], v[14:17]
	v_mfma_f32_16x16x32_bf16 v[10:13], v[138:141], v[224:227], v[10:13]
	v_mfma_f32_16x16x32_bf16 v[62:65], v[134:137], v[188:191], v[62:65]
	v_mfma_f32_16x16x32_bf16 v[58:61], v[142:145], v[188:191], v[58:61]
	v_mfma_f32_16x16x32_bf16 v[46:49], v[134:137], v[212:215], v[46:49]
	v_mfma_f32_16x16x32_bf16 v[42:45], v[142:145], v[212:215], v[42:45]
	v_mfma_f32_16x16x32_bf16 v[30:33], v[134:137], v[220:223], v[30:33]
	v_mfma_f32_16x16x32_bf16 v[26:29], v[142:145], v[220:223], v[26:29]
	v_mfma_f32_16x16x32_bf16 v[14:17], v[134:137], v[228:231], v[14:17]
	v_mfma_f32_16x16x32_bf16 v[10:13], v[142:145], v[228:231], v[10:13]
	v_mfma_f32_16x16x32_bf16 v[54:57], v[146:149], v[184:187], v[54:57]
	v_mfma_f32_16x16x32_bf16 v[50:53], v[176:179], v[184:187], v[50:53]
	v_mfma_f32_16x16x32_bf16 v[38:41], v[146:149], v[208:211], v[38:41]
	v_mfma_f32_16x16x32_bf16 v[34:37], v[176:179], v[208:211], v[34:37]
	v_mfma_f32_16x16x32_bf16 v[22:25], v[146:149], v[216:219], v[22:25]
	v_mfma_f32_16x16x32_bf16 v[18:21], v[176:179], v[216:219], v[18:21]
	v_mfma_f32_16x16x32_bf16 v[6:9], v[146:149], v[224:227], v[6:9]
	v_mfma_f32_16x16x32_bf16 v[2:5], v[176:179], v[224:227], v[2:5]
	v_mfma_f32_16x16x32_bf16 v[54:57], v[150:153], v[188:191], v[54:57]
	v_mfma_f32_16x16x32_bf16 v[50:53], v[180:183], v[188:191], v[50:53]
	v_mfma_f32_16x16x32_bf16 v[38:41], v[150:153], v[212:215], v[38:41]
	v_mfma_f32_16x16x32_bf16 v[34:37], v[180:183], v[212:215], v[34:37]
	v_mfma_f32_16x16x32_bf16 v[22:25], v[150:153], v[220:223], v[22:25]
	v_mfma_f32_16x16x32_bf16 v[18:21], v[180:183], v[220:223], v[18:21]
	s_setprio 2
	v_mfma_f32_16x16x32_bf16 v[6:9], v[150:153], v[228:231], v[6:9]
	s_barrier
	v_mfma_f32_16x16x32_bf16 v[2:5], v[180:183], v[228:231], v[2:5]
	s_setprio 0
	s_add_i32 s59, 0, 0x18000
	s_add_i32 s86, 0, 0x1c000
	v_add_u32_e32 v142, s59, v205
	v_add_u32_e32 v180, s86, v205
	ds_read_b128 v[130:133], v142
	ds_read_b128 v[134:137], v142 offset:1024
	ds_read_b128 v[138:141], v142 offset:2048
	ds_read_b128 v[142:145], v142 offset:3072
	ds_read_b128 v[146:149], v180
	ds_read_b128 v[150:153], v180 offset:1024
	ds_read_b128 v[176:179], v180 offset:2048
	ds_read_b128 v[180:183], v180 offset:3072
	s_add_u32 s38, s70, s14
	s_addc_u32 s39, s71, 0
	s_mov_b32 m0, s75
	v_lshl_add_u64 v[240:241], s[38:39], 0, v[170:171]
	ds_read_b128 v[184:187], v207 offset:32768
	ds_read_b128 v[188:191], v207 offset:33792
	ds_read_b128 v[208:211], v207 offset:34816
	ds_read_b128 v[212:215], v207 offset:35840
	ds_read_b128 v[216:219], v207 offset:36864
	ds_read_b128 v[220:223], v207 offset:37888
	ds_read_b128 v[224:227], v207 offset:38912
	ds_read_b128 v[228:231], v207 offset:39936
	global_load_lds_dwordx4 v[240:241], off
	v_lshl_add_u64 v[240:241], s[38:39], 0, v[168:169]
	s_mov_b32 m0, s76
	s_nop 0
	global_load_lds_dwordx4 v[240:241], off
	s_waitcnt vmcnt(8)
	s_waitcnt lgkmcnt(0)
	s_setprio 1
	s_barrier
	v_mfma_f32_16x16x32_bf16 v[126:129], v[130:133], v[184:187], v[126:129]
	v_mfma_f32_16x16x32_bf16 v[122:125], v[138:141], v[184:187], v[122:125]
	v_mfma_f32_16x16x32_bf16 v[110:113], v[130:133], v[208:211], v[110:113]
	v_mfma_f32_16x16x32_bf16 v[106:109], v[138:141], v[208:211], v[106:109]
	v_mfma_f32_16x16x32_bf16 v[94:97], v[130:133], v[216:219], v[94:97]
	v_mfma_f32_16x16x32_bf16 v[90:93], v[138:141], v[216:219], v[90:93]
	v_mfma_f32_16x16x32_bf16 v[78:81], v[130:133], v[224:227], v[78:81]
	v_mfma_f32_16x16x32_bf16 v[74:77], v[138:141], v[224:227], v[74:77]
	v_mfma_f32_16x16x32_bf16 v[126:129], v[134:137], v[188:191], v[126:129]
	v_mfma_f32_16x16x32_bf16 v[122:125], v[142:145], v[188:191], v[122:125]
	v_mfma_f32_16x16x32_bf16 v[110:113], v[134:137], v[212:215], v[110:113]
	v_mfma_f32_16x16x32_bf16 v[106:109], v[142:145], v[212:215], v[106:109]
	v_mfma_f32_16x16x32_bf16 v[94:97], v[134:137], v[220:223], v[94:97]
	v_mfma_f32_16x16x32_bf16 v[90:93], v[142:145], v[220:223], v[90:93]
	v_mfma_f32_16x16x32_bf16 v[78:81], v[134:137], v[228:231], v[78:81]
	v_mfma_f32_16x16x32_bf16 v[74:77], v[142:145], v[228:231], v[74:77]
	v_mfma_f32_16x16x32_bf16 v[118:121], v[146:149], v[184:187], v[118:121]
	v_mfma_f32_16x16x32_bf16 v[114:117], v[176:179], v[184:187], v[114:117]
	v_mfma_f32_16x16x32_bf16 v[102:105], v[146:149], v[208:211], v[102:105]
	v_mfma_f32_16x16x32_bf16 v[98:101], v[176:179], v[208:211], v[98:101]
	v_mfma_f32_16x16x32_bf16 v[86:89], v[146:149], v[216:219], v[86:89]
	v_mfma_f32_16x16x32_bf16 v[82:85], v[176:179], v[216:219], v[82:85]
	v_mfma_f32_16x16x32_bf16 v[70:73], v[146:149], v[224:227], v[70:73]
	v_mfma_f32_16x16x32_bf16 v[66:69], v[176:179], v[224:227], v[66:69]
	v_mfma_f32_16x16x32_bf16 v[118:121], v[150:153], v[188:191], v[118:121]
	v_mfma_f32_16x16x32_bf16 v[114:117], v[180:183], v[188:191], v[114:117]
	v_mfma_f32_16x16x32_bf16 v[102:105], v[150:153], v[212:215], v[102:105]
	v_mfma_f32_16x16x32_bf16 v[98:101], v[180:183], v[212:215], v[98:101]
	v_mfma_f32_16x16x32_bf16 v[86:89], v[150:153], v[220:223], v[86:89]
	v_mfma_f32_16x16x32_bf16 v[82:85], v[180:183], v[220:223], v[82:85]
	s_setprio 2
	v_mfma_f32_16x16x32_bf16 v[70:73], v[150:153], v[228:231], v[70:73]
	s_barrier
; #define PG8_STAGE(bufoff, gbase, voff) do { _Pragma("unroll") for (int _i = 0; _i < 2; ++_i) \
;         __builtin_amdgcn_global_load_lds((const unsigned*)((const char*)(gbase) + (voff)[_i]), (PG8_LAS unsigned*)(lds + (bufoff) + ldsw + _i * 8192), 16, 0, 0); } while (0)
; #define PG8_LDA(dst, b, h) do { _Pragma("unroll") for (int m = 0; m < 4; ++m) _Pragma("unroll") for (int k = 0; k < 2; ++k) dst[m][k] = *(const PG8_LAS bf16x8*)(lds + PG8_SA(b, h) + aoff + m * 2048 + k * 1024); } while (0)
; #define PG8_MMA(ai, bj, At, Bt) do { __builtin_amdgcn_s_setprio(1); _Pragma("unroll") for (int m = 0; m < 4; ++m) _Pragma("unroll") for (int n = 0; n < 2; ++n) _Pragma("unroll") for (int k = 0; k < 2; ++k) \
;         acc[ai][bj][m][n] = __builtin_amdgcn_mfma_f32_16x16x32_bf16(Bt[n][k], At[m][k], acc[ai][bj][m][n], 0, 0, 0); __builtin_amdgcn_s_setprio(0); } while (0)
; #define PG8_WAIT_V(n) asm volatile("s_waitcnt vmcnt(" #n ")" ::: "memory")
; #define PG8_WAIT_L(n) asm volatile("s_waitcnt lgkmcnt(" #n ")" ::: "memory")
; #define PG8_BAR __builtin_amdgcn_s_barrier()
; #define PG8_SCHED __builtin_amdgcn_sched_barrier(0)
; template <class Epi, class Sched, bool ALIGN_EPI = false, bool SP2 = false>
; __device__ __forceinline__ void gemm_phase(PG8_LAS unsigned char* lds, const Gemm g, const Sched& S, const Epi& E, const int tid) {
;     ...
;             PG8_LDA(At, 1, 1); PG8_STAGE(PG8_SB(1, 0), b3, voffB); PG8_STAGE(PG8_SB(1, 1), b3 + hstep, voffB); PG8_STAGE(PG8_SA(1, 0), a3, voffA);
;             PG8_WAIT_V(8); PG8_WAIT_L(0); PG8_BAR; PG8_MMA(1, 0, At, B0); PG8_MMA(1, 1, At, B1); PG8_BAR; PG8_SCHED;
;     ...
;         if constexpr (ALIGN_EPI) { if (wr == 0) PG8_BAR; }
	v_mfma_f32_16x16x32_bf16 v[66:69], v[180:183], v[228:231], v[66:69]
	s_setprio 0
	s_add_i32 s38, s59, s72
	v_lshl_add_u64 v[192:193], v[192:193], 0, s[56:57]
	s_mov_b32 m0, s38
	ds_read_b128 v[184:187], v207 offset:49152
	ds_read_b128 v[188:191], v207 offset:50176
	ds_read_b128 v[208:211], v207 offset:51200
	ds_read_b128 v[212:215], v207 offset:52224
	ds_read_b128 v[216:219], v207 offset:53248
	ds_read_b128 v[220:223], v207 offset:54272
	ds_read_b128 v[224:227], v207 offset:55296
	ds_read_b128 v[228:231], v207 offset:56320
	global_load_lds_dwordx4 v[192:193], off
	v_lshl_add_u64 v[192:193], v[194:195], 0, s[56:57]
	s_add_i32 m0, s38, 0x2000
	s_add_i32 s38, s86, s72
	global_load_lds_dwordx4 v[192:193], off
	v_lshl_add_u64 v[192:193], v[232:233], 0, s[56:57]
	s_mov_b32 m0, s38
	s_nop 0
	global_load_lds_dwordx4 v[192:193], off
	v_lshl_add_u64 v[192:193], v[234:235], 0, s[56:57]
	s_add_i32 m0, s38, 0x2000
	s_nop 0
	global_load_lds_dwordx4 v[192:193], off
	v_lshl_add_u64 v[192:193], v[236:237], 0, s[56:57]
	s_mov_b32 m0, s79
	s_nop 0
	global_load_lds_dwordx4 v[192:193], off
	v_lshl_add_u64 v[192:193], v[238:239], 0, s[56:57]
	s_mov_b32 m0, s80
	s_nop 0
	global_load_lds_dwordx4 v[192:193], off
	s_waitcnt vmcnt(8)
	s_waitcnt lgkmcnt(0)
	s_setprio 1
	s_barrier
	v_mfma_f32_16x16x32_bf16 v[62:65], v[130:133], v[184:187], v[62:65]
	v_mfma_f32_16x16x32_bf16 v[58:61], v[138:141], v[184:187], v[58:61]
	v_mfma_f32_16x16x32_bf16 v[46:49], v[130:133], v[208:211], v[46:49]
	v_mfma_f32_16x16x32_bf16 v[42:45], v[138:141], v[208:211], v[42:45]
	v_mfma_f32_16x16x32_bf16 v[30:33], v[130:133], v[216:219], v[30:33]
	v_mfma_f32_16x16x32_bf16 v[26:29], v[138:141], v[216:219], v[26:29]
	v_mfma_f32_16x16x32_bf16 v[14:17], v[130:133], v[224:227], v[14:17]
	v_mfma_f32_16x16x32_bf16 v[10:13], v[138:141], v[224:227], v[10:13]
	v_mfma_f32_16x16x32_bf16 v[62:65], v[134:137], v[188:191], v[62:65]
	v_mfma_f32_16x16x32_bf16 v[58:61], v[142:145], v[188:191], v[58:61]
	v_mfma_f32_16x16x32_bf16 v[46:49], v[134:137], v[212:215], v[46:49]
	v_mfma_f32_16x16x32_bf16 v[42:45], v[142:145], v[212:215], v[42:45]
	v_mfma_f32_16x16x32_bf16 v[30:33], v[134:137], v[220:223], v[30:33]
	v_mfma_f32_16x16x32_bf16 v[26:29], v[142:145], v[220:223], v[26:29]
	v_mfma_f32_16x16x32_bf16 v[14:17], v[134:137], v[228:231], v[14:17]
	v_mfma_f32_16x16x32_bf16 v[10:13], v[142:145], v[228:231], v[10:13]
	v_mfma_f32_16x16x32_bf16 v[54:57], v[146:149], v[184:187], v[54:57]
	v_mfma_f32_16x16x32_bf16 v[50:53], v[176:179], v[184:187], v[50:53]
	v_mfma_f32_16x16x32_bf16 v[38:41], v[146:149], v[208:211], v[38:41]
	v_mfma_f32_16x16x32_bf16 v[34:37], v[176:179], v[208:211], v[34:37]
	v_mfma_f32_16x16x32_bf16 v[22:25], v[146:149], v[216:219], v[22:25]
	v_mfma_f32_16x16x32_bf16 v[18:21], v[176:179], v[216:219], v[18:21]
	v_mfma_f32_16x16x32_bf16 v[6:9], v[146:149], v[224:227], v[6:9]
	v_mfma_f32_16x16x32_bf16 v[2:5], v[176:179], v[224:227], v[2:5]
	v_mfma_f32_16x16x32_bf16 v[54:57], v[150:153], v[188:191], v[54:57]
	v_mfma_f32_16x16x32_bf16 v[50:53], v[180:183], v[188:191], v[50:53]
	v_mfma_f32_16x16x32_bf16 v[38:41], v[150:153], v[212:215], v[38:41]
	v_mfma_f32_16x16x32_bf16 v[34:37], v[180:183], v[212:215], v[34:37]
	v_mfma_f32_16x16x32_bf16 v[22:25], v[150:153], v[220:223], v[22:25]
	v_mfma_f32_16x16x32_bf16 v[18:21], v[180:183], v[220:223], v[18:21]
	s_setprio 2
	v_mfma_f32_16x16x32_bf16 v[6:9], v[150:153], v[228:231], v[6:9]
	s_barrier
	v_mfma_f32_16x16x32_bf16 v[2:5], v[180:183], v[228:231], v[2:5]
	s_setprio 0
	s_add_u32 s68, s68, 0x100
	s_addc_u32 s69, s69, 0
	s_add_u32 s50, s50, 0x100
	s_addc_u32 s51, s51, 0
	s_cmp_ge_u32 s85, s78
	s_mov_b32 s70, s85
	s_cbranch_scc0 .LBB0_618
	s_and_b64 vcc, exec, s[22:23]
	s_cbranch_vccz .LBB0_621
	s_barrier
